# hidden activations stream marked nt (MLP1 epilogue stores, MLP2 X-operand DMA loads) instead of sc1 write-through
# speedup vs baseline: 1.0272x; 1.0031x over previous
.LBB0_1601:
	v_mov_b32_e32 v0, v174
	v_mov_b32_e32 v133, v177
	v_mov_b32_e32 v132, v175
	v_mov_b32_e32 v134, v180
	v_mov_b32_e32 v162, v176
	v_mov_b32_e32 v135, v179
	v_mov_b32_e32 v163, v173
	ds_read2_b32 v[150:151], v185 offset1:32
	ds_read2_b32 v[130:131], v185 offset0:64 offset1:96
	s_lshl_b32 s1, s6, 8
	v_readfirstlane_b32 s0, v134
	v_lshlrev_b32_e32 v0, 14, v0
	v_lshlrev_b32_e32 v134, 7, v162
	v_lshlrev_b32_e32 v133, 3, v133
	v_ashrrev_i32_e32 v148, 3, v163
	v_add3_u32 v133, v0, v134, v133
	v_xor_b32_e32 v134, v148, v163
	v_lshlrev_b32_e32 v134, 4, v134
	v_add_u32_e32 v142, 32, v148
	v_and_or_b32 v0, v134, s55, v0
	v_ashrrev_i32_e32 v149, 31, v148
	v_ashrrev_i32_e32 v143, 31, v142
	v_lshlrev_b32_e32 v152, 6, v135
	v_lshl_add_u32 v154, v148, 7, v0
	v_lshlrev_b64 v[134:135], 13, v[148:149]
	v_add_u32_e32 v136, 8, v148
	v_add_u32_e32 v138, 16, v148
	v_add_u32_e32 v140, 24, v148
	v_lshl_add_u32 v158, v142, 7, v0
	v_lshlrev_b64 v[144:145], 13, v[142:143]
	v_add_u32_e32 v142, 40, v148
	v_add_u32_e32 v146, 48, v148
	v_add_u32_e32 v148, 56, v148
	v_lshl_add_u32 v155, v136, 7, v0
	v_lshl_add_u32 v156, v138, 7, v0
	v_lshl_add_u32 v157, v140, 7, v0
	v_lshl_add_u32 v159, v142, 7, v0
	v_lshl_add_u32 v160, v146, 7, v0
	v_lshl_add_u32 v161, v148, 7, v0
	s_waitcnt lgkmcnt(1)
	v_mul_f32_e32 v0, v98, v150
	v_mul_f32_e32 v98, v99, v150
	v_max_f32_e32 v0, 0, v0
	v_max_f32_e32 v98, 0, v98
	v_mul_f32_e32 v99, v100, v150
	v_mul_f32_e32 v100, v101, v150
	v_max_f32_e32 v99, 0, v99
	v_max_f32_e32 v100, 0, v100
	v_mul_f32_e32 v0, v0, v0
	v_mul_f32_e32 v98, v98, v98
	v_cvt_pk_bf16_f32 v98, v0, v98
	v_mul_f32_e32 v0, v99, v99
	v_mul_f32_e32 v99, v100, v100
	v_cvt_pk_bf16_f32 v99, v0, v99
	v_lshlrev_b32_e32 v0, 4, v162
	v_and_b32_e32 v0, 0x70, v0
	v_add_u32_e32 v100, v133, v0
	ds_write_b64 v100, v[98:99]
	v_mul_f32_e32 v98, v102, v150
	v_mul_f32_e32 v99, v103, v150
	v_max_f32_e32 v98, 0, v98
	v_max_f32_e32 v99, 0, v99
	v_mul_f32_e32 v101, v104, v150
	v_mul_f32_e32 v102, v105, v150
	v_max_f32_e32 v101, 0, v101
	v_max_f32_e32 v102, 0, v102
	v_mul_f32_e32 v98, v98, v98
	v_mul_f32_e32 v99, v99, v99
	v_cvt_pk_bf16_f32 v98, v98, v99
	v_mul_f32_e32 v99, v101, v101
	v_mul_f32_e32 v101, v102, v102
	v_cvt_pk_bf16_f32 v99, v99, v101
	v_xad_u32 v101, v0, 16, v133
	ds_write_b64 v101, v[98:99]
	v_mul_f32_e32 v98, v106, v150
	v_mul_f32_e32 v99, v107, v150
	v_max_f32_e32 v98, 0, v98
	v_max_f32_e32 v99, 0, v99
	v_mul_f32_e32 v102, v108, v150
	v_mul_f32_e32 v103, v109, v150
	v_max_f32_e32 v102, 0, v102
	v_max_f32_e32 v103, 0, v103
	v_mul_f32_e32 v98, v98, v98
	v_mul_f32_e32 v99, v99, v99
	v_cvt_pk_bf16_f32 v98, v98, v99
	v_mul_f32_e32 v99, v102, v102
	v_mul_f32_e32 v102, v103, v103
	v_cvt_pk_bf16_f32 v99, v99, v102
	v_xad_u32 v102, v0, 32, v133
	ds_write_b64 v102, v[98:99]
	v_mul_f32_e32 v98, v110, v150
	v_mul_f32_e32 v99, v111, v150
	v_max_f32_e32 v98, 0, v98
	v_max_f32_e32 v99, 0, v99
	v_mul_f32_e32 v103, v112, v150
	v_mul_f32_e32 v104, v113, v150
	v_max_f32_e32 v103, 0, v103
	v_max_f32_e32 v104, 0, v104
	v_mul_f32_e32 v98, v98, v98
	v_mul_f32_e32 v99, v99, v99
	v_cvt_pk_bf16_f32 v98, v98, v99
	v_mul_f32_e32 v99, v103, v103
	v_mul_f32_e32 v103, v104, v104
	v_cvt_pk_bf16_f32 v99, v99, v103
	v_xad_u32 v103, v0, 48, v133
	ds_write_b64 v103, v[98:99]
	v_mul_f32_e32 v98, v114, v150
	v_mul_f32_e32 v99, v115, v150
	v_max_f32_e32 v98, 0, v98
	v_max_f32_e32 v99, 0, v99
	v_mul_f32_e32 v104, v116, v150
	v_mul_f32_e32 v105, v117, v150
	v_max_f32_e32 v104, 0, v104
	v_max_f32_e32 v105, 0, v105
	v_mul_f32_e32 v98, v98, v98
	v_mul_f32_e32 v99, v99, v99
	v_cvt_pk_bf16_f32 v98, v98, v99
	v_mul_f32_e32 v99, v104, v104
	v_mul_f32_e32 v104, v105, v105
	v_cvt_pk_bf16_f32 v99, v99, v104
	v_xad_u32 v104, v0, 64, v133
	ds_write_b64 v104, v[98:99]
	v_mul_f32_e32 v98, v118, v150
	v_mul_f32_e32 v99, v119, v150
	v_max_f32_e32 v98, 0, v98
	v_max_f32_e32 v99, 0, v99
	v_mul_f32_e32 v105, v120, v150
	v_mul_f32_e32 v106, v121, v150
	v_max_f32_e32 v105, 0, v105
	v_max_f32_e32 v106, 0, v106
	v_mul_f32_e32 v98, v98, v98
	v_mul_f32_e32 v99, v99, v99
	v_cvt_pk_bf16_f32 v98, v98, v99
	v_mul_f32_e32 v99, v105, v105
	v_mul_f32_e32 v105, v106, v106
	v_cvt_pk_bf16_f32 v99, v99, v105
	v_xad_u32 v105, v0, s70, v133
	ds_write_b64 v105, v[98:99]
	v_mul_f32_e32 v98, v122, v150
	v_mul_f32_e32 v99, v123, v150
	v_max_f32_e32 v98, 0, v98
	v_max_f32_e32 v99, 0, v99
	v_mul_f32_e32 v106, v124, v150
	v_mul_f32_e32 v107, v125, v150
	v_max_f32_e32 v106, 0, v106
	v_max_f32_e32 v107, 0, v107
	v_mul_f32_e32 v98, v98, v98
	v_mul_f32_e32 v99, v99, v99
	v_cvt_pk_bf16_f32 v98, v98, v99
	v_mul_f32_e32 v99, v106, v106
	v_mul_f32_e32 v106, v107, v107
	v_cvt_pk_bf16_f32 v99, v99, v106
	v_xad_u32 v106, v0, s63, v133
	ds_write_b64 v106, v[98:99]
	v_mul_f32_e32 v98, v126, v150
	v_mul_f32_e32 v99, v127, v150
	v_max_f32_e32 v98, 0, v98
	v_max_f32_e32 v99, 0, v99
	v_mul_f32_e32 v107, v128, v150
	v_mul_f32_e32 v108, v129, v150
	v_max_f32_e32 v107, 0, v107
	v_max_f32_e32 v108, 0, v108
	v_mul_f32_e32 v98, v98, v98
	v_mul_f32_e32 v99, v99, v99
	v_cvt_pk_bf16_f32 v98, v98, v99
	v_mul_f32_e32 v99, v107, v107
	v_mul_f32_e32 v107, v108, v108
	v_cvt_pk_bf16_f32 v99, v99, v107
	v_xad_u32 v107, v0, s55, v133
	v_mul_f32_e32 v0, v82, v151
	v_mul_f32_e32 v82, v83, v151
	v_max_f32_e32 v0, 0, v0
	v_max_f32_e32 v82, 0, v82
	v_mul_f32_e32 v83, v84, v151
	v_mul_f32_e32 v84, v85, v151
	v_max_f32_e32 v83, 0, v83
	v_max_f32_e32 v84, 0, v84
	v_mul_f32_e32 v0, v0, v0
	v_mul_f32_e32 v82, v82, v82
	v_cvt_pk_bf16_f32 v82, v0, v82
	v_mul_f32_e32 v0, v83, v83
	v_mul_f32_e32 v83, v84, v84
	v_cvt_pk_bf16_f32 v83, v0, v83
	ds_write_b64 v100, v[82:83] offset:4096
	v_mul_f32_e32 v0, v86, v151
	v_mul_f32_e32 v82, v87, v151
	v_max_f32_e32 v0, 0, v0
	v_max_f32_e32 v82, 0, v82
	v_mul_f32_e32 v83, v88, v151
	v_mul_f32_e32 v84, v89, v151
	v_max_f32_e32 v83, 0, v83
	v_max_f32_e32 v84, 0, v84
	v_mul_f32_e32 v0, v0, v0
	v_mul_f32_e32 v82, v82, v82
	v_cvt_pk_bf16_f32 v82, v0, v82
	v_mul_f32_e32 v0, v83, v83
	v_mul_f32_e32 v83, v84, v84
	v_cvt_pk_bf16_f32 v83, v0, v83
	ds_write_b64 v101, v[82:83] offset:4096
	v_mul_f32_e32 v0, v90, v151
	v_mul_f32_e32 v82, v91, v151
	v_max_f32_e32 v0, 0, v0
	v_max_f32_e32 v82, 0, v82
	v_mul_f32_e32 v83, v92, v151
	v_mul_f32_e32 v84, v93, v151
	v_max_f32_e32 v83, 0, v83
	v_max_f32_e32 v84, 0, v84
	v_mul_f32_e32 v0, v0, v0
	v_mul_f32_e32 v82, v82, v82
	v_cvt_pk_bf16_f32 v82, v0, v82
	v_mul_f32_e32 v0, v83, v83
	v_mul_f32_e32 v83, v84, v84
	v_cvt_pk_bf16_f32 v83, v0, v83
	ds_write_b64 v102, v[82:83] offset:4096
	v_mul_f32_e32 v0, v94, v151
	v_mul_f32_e32 v82, v95, v151
	v_max_f32_e32 v0, 0, v0
	v_max_f32_e32 v82, 0, v82
	v_mul_f32_e32 v83, v96, v151
	v_mul_f32_e32 v84, v97, v151
	v_max_f32_e32 v83, 0, v83
	v_max_f32_e32 v84, 0, v84
	v_mul_f32_e32 v0, v0, v0
	v_mul_f32_e32 v82, v82, v82
	v_cvt_pk_bf16_f32 v82, v0, v82
	v_mul_f32_e32 v0, v83, v83
	v_mul_f32_e32 v83, v84, v84
	v_cvt_pk_bf16_f32 v83, v0, v83
	v_mul_f32_e32 v0, v66, v151
	v_mul_f32_e32 v66, v67, v151
	v_max_f32_e32 v0, 0, v0
	v_max_f32_e32 v66, 0, v66
	v_mul_f32_e32 v67, v68, v151
	v_mul_f32_e32 v68, v69, v151
	v_max_f32_e32 v67, 0, v67
	v_max_f32_e32 v68, 0, v68
	v_mul_f32_e32 v0, v0, v0
	v_mul_f32_e32 v66, v66, v66
	v_cvt_pk_bf16_f32 v66, v0, v66
	v_mul_f32_e32 v0, v67, v67
	v_mul_f32_e32 v67, v68, v68
	v_cvt_pk_bf16_f32 v67, v0, v67
	ds_write_b64 v103, v[82:83] offset:4096
	ds_write_b64 v104, v[66:67] offset:4096
	v_mul_f32_e32 v0, v70, v151
	v_mul_f32_e32 v66, v71, v151
	v_max_f32_e32 v0, 0, v0
	v_max_f32_e32 v66, 0, v66
	v_mul_f32_e32 v67, v72, v151
	v_mul_f32_e32 v68, v73, v151
	v_max_f32_e32 v67, 0, v67
	v_max_f32_e32 v68, 0, v68
	v_mul_f32_e32 v0, v0, v0
	v_mul_f32_e32 v66, v66, v66
	v_cvt_pk_bf16_f32 v66, v0, v66
	v_mul_f32_e32 v0, v67, v67
	v_mul_f32_e32 v67, v68, v68
	v_cvt_pk_bf16_f32 v67, v0, v67
	ds_write_b64 v105, v[66:67] offset:4096
	v_mul_f32_e32 v0, v74, v151
	v_mul_f32_e32 v66, v75, v151
	v_max_f32_e32 v0, 0, v0
	v_max_f32_e32 v66, 0, v66
	v_mul_f32_e32 v67, v76, v151
	v_mul_f32_e32 v68, v77, v151
	v_max_f32_e32 v67, 0, v67
	v_max_f32_e32 v68, 0, v68
	v_mul_f32_e32 v0, v0, v0
	v_mul_f32_e32 v66, v66, v66
	v_cvt_pk_bf16_f32 v66, v0, v66
	v_mul_f32_e32 v0, v67, v67
	v_mul_f32_e32 v67, v68, v68
	v_cvt_pk_bf16_f32 v67, v0, v67
	ds_write_b64 v106, v[66:67] offset:4096
	v_mul_f32_e32 v0, v78, v151
	v_mul_f32_e32 v66, v79, v151
	v_max_f32_e32 v0, 0, v0
	v_max_f32_e32 v66, 0, v66
	v_mul_f32_e32 v67, v80, v151
	v_mul_f32_e32 v68, v81, v151
	v_max_f32_e32 v67, 0, v67
	v_max_f32_e32 v68, 0, v68
	v_mul_f32_e32 v0, v0, v0
	v_mul_f32_e32 v66, v66, v66
	s_lshl_b32 s0, s0, 7
	v_lshl_add_u32 v132, v132, 7, s4
	v_cvt_pk_bf16_f32 v66, v0, v66
	v_mul_f32_e32 v0, v67, v67
	v_mul_f32_e32 v67, v68, v68
	s_add_i32 s0, s0, s1
	v_cvt_pk_bf16_f32 v67, v0, v67
	v_ashrrev_i32_e32 v133, 31, v132
	v_readlane_b32 s4, v250, 48
	s_ashr_i32 s1, s0, 31
	ds_write_b64 v107, v[66:67] offset:4096
	v_lshlrev_b64 v[66:67], 13, v[132:133]
	v_readlane_b32 s5, v250, 49
	v_ashrrev_i32_e32 v153, 31, v152
	s_lshl_b64 s[0:1], s[0:1], 1
	v_lshl_add_u64 v[66:67], s[4:5], 0, v[66:67]
	ds_write_b64 v107, v[98:99]
	v_lshl_add_u64 v[68:69], v[66:67], 0, s[0:1]
	v_lshlrev_b64 v[66:67], 1, v[152:153]
	v_lshl_add_u64 v[72:73], v[68:69], 0, v[66:67]
	ds_read_b128 v[68:71], v154
	v_lshlrev_b32_e32 v0, 4, v163
	v_and_b32_e32 v0, 0x70, v0
	v_lshl_add_u64 v[80:81], v[72:73], 0, v[0:1]
	ds_read_b128 v[72:75], v155
	v_lshl_add_u64 v[76:77], v[80:81], 0, v[134:135]
	s_waitcnt lgkmcnt(1)
	global_store_dwordx4 v[76:77], v[68:71], off nt
	ds_read_b128 v[68:71], v156
	v_ashrrev_i32_e32 v137, 31, v136
	v_lshlrev_b64 v[136:137], 13, v[136:137]
	v_ashrrev_i32_e32 v139, 31, v138
	v_lshlrev_b64 v[138:139], 13, v[138:139]
	v_lshl_add_u64 v[76:77], v[80:81], 0, v[136:137]
	s_waitcnt lgkmcnt(1)
	global_store_dwordx4 v[76:77], v[72:75], off nt
	ds_read_b128 v[72:75], v157
	v_lshl_add_u64 v[76:77], v[80:81], 0, v[138:139]
	s_waitcnt lgkmcnt(1)
	global_store_dwordx4 v[76:77], v[68:71], off nt
	ds_read_b128 v[68:71], v158
	v_mul_f32_e32 v18, v18, v131
	v_mul_f32_e32 v19, v19, v131
	v_ashrrev_i32_e32 v141, 31, v140
	v_max_f32_e32 v18, 0, v18
	v_max_f32_e32 v19, 0, v19
	v_mul_f32_e32 v20, v20, v131
	v_mul_f32_e32 v21, v21, v131
	v_lshlrev_b64 v[140:141], 13, v[140:141]
	v_max_f32_e32 v20, 0, v20
	v_max_f32_e32 v21, 0, v21
	v_mul_f32_e32 v18, v18, v18
	v_mul_f32_e32 v19, v19, v19
	v_lshl_add_u64 v[76:77], v[80:81], 0, v[140:141]
	v_mul_f32_e32 v50, v50, v130
	v_mul_f32_e32 v51, v51, v130
	v_cvt_pk_bf16_f32 v18, v18, v19
	v_mul_f32_e32 v19, v20, v20
	v_mul_f32_e32 v20, v21, v21
	s_waitcnt lgkmcnt(1)
	global_store_dwordx4 v[76:77], v[72:75], off nt
	v_lshl_add_u64 v[76:77], v[80:81], 0, v[144:145]
	v_max_f32_e32 v50, 0, v50
	v_max_f32_e32 v51, 0, v51
	v_mul_f32_e32 v52, v52, v130
	v_mul_f32_e32 v53, v53, v130
	v_cvt_pk_bf16_f32 v19, v19, v20
	ds_read_b128 v[72:75], v159
	s_waitcnt lgkmcnt(1)
	global_store_dwordx4 v[76:77], v[68:71], off nt
	ds_read_b128 v[68:71], v160
	ds_read_b128 v[76:79], v161
	v_max_f32_e32 v52, 0, v52
	v_max_f32_e32 v53, 0, v53
	v_mul_f32_e32 v50, v50, v50
	v_mul_f32_e32 v51, v51, v51
	ds_write_b64 v100, v[18:19] offset:4096
	v_mul_f32_e32 v18, v22, v131
	v_mul_f32_e32 v19, v23, v131
	v_cvt_pk_bf16_f32 v50, v50, v51
	v_mul_f32_e32 v51, v52, v52
	v_mul_f32_e32 v52, v53, v53
	v_max_f32_e32 v18, 0, v18
	v_max_f32_e32 v19, 0, v19
	v_mul_f32_e32 v20, v24, v131
	v_mul_f32_e32 v21, v25, v131
	v_cvt_pk_bf16_f32 v51, v51, v52
	v_max_f32_e32 v20, 0, v20
	v_max_f32_e32 v21, 0, v21
	v_mul_f32_e32 v18, v18, v18
	v_mul_f32_e32 v19, v19, v19
	ds_write_b64 v100, v[50:51]
	v_mul_f32_e32 v50, v54, v130
	v_mul_f32_e32 v51, v55, v130
	v_cvt_pk_bf16_f32 v18, v18, v19
	v_mul_f32_e32 v19, v20, v20
	v_mul_f32_e32 v20, v21, v21
	v_max_f32_e32 v50, 0, v50
	v_max_f32_e32 v51, 0, v51
	v_mul_f32_e32 v52, v56, v130
	v_mul_f32_e32 v53, v57, v130
	v_cvt_pk_bf16_f32 v19, v19, v20
	v_max_f32_e32 v52, 0, v52
	v_max_f32_e32 v53, 0, v53
	v_mul_f32_e32 v50, v50, v50
	v_mul_f32_e32 v51, v51, v51
	ds_write_b64 v101, v[18:19] offset:4096
	v_mul_f32_e32 v18, v26, v131
	v_mul_f32_e32 v19, v27, v131
	v_cvt_pk_bf16_f32 v50, v50, v51
	v_mul_f32_e32 v51, v52, v52
	v_mul_f32_e32 v52, v53, v53
	v_max_f32_e32 v18, 0, v18
	v_max_f32_e32 v19, 0, v19
	v_mul_f32_e32 v20, v28, v131
	v_mul_f32_e32 v21, v29, v131
	v_cvt_pk_bf16_f32 v51, v51, v52
	v_max_f32_e32 v20, 0, v20
	v_max_f32_e32 v21, 0, v21
	v_mul_f32_e32 v18, v18, v18
	v_mul_f32_e32 v19, v19, v19
	ds_write_b64 v101, v[50:51]
	v_mul_f32_e32 v50, v58, v130
	v_mul_f32_e32 v51, v59, v130
	v_cvt_pk_bf16_f32 v18, v18, v19
	v_mul_f32_e32 v19, v20, v20
	v_mul_f32_e32 v20, v21, v21
	v_max_f32_e32 v50, 0, v50
	v_max_f32_e32 v51, 0, v51
	v_mul_f32_e32 v52, v60, v130
	v_mul_f32_e32 v53, v61, v130
	v_cvt_pk_bf16_f32 v19, v19, v20
	v_max_f32_e32 v52, 0, v52
	v_max_f32_e32 v53, 0, v53
	v_mul_f32_e32 v50, v50, v50
	v_mul_f32_e32 v51, v51, v51
	ds_write_b64 v102, v[18:19] offset:4096
	v_mul_f32_e32 v18, v30, v131
	v_mul_f32_e32 v19, v31, v131
	v_mul_f32_e32 v2, v2, v131
	v_mul_f32_e32 v3, v3, v131
	v_cvt_pk_bf16_f32 v50, v50, v51
	v_mul_f32_e32 v51, v52, v52
	v_mul_f32_e32 v52, v53, v53
	v_max_f32_e32 v18, 0, v18
	v_max_f32_e32 v19, 0, v19
	v_mul_f32_e32 v20, v32, v131
	v_mul_f32_e32 v21, v33, v131
	v_max_f32_e32 v2, 0, v2
	v_max_f32_e32 v3, 0, v3
	v_mul_f32_e32 v4, v4, v131
	v_mul_f32_e32 v5, v5, v131
	v_cvt_pk_bf16_f32 v51, v51, v52
	v_max_f32_e32 v20, 0, v20
	v_max_f32_e32 v21, 0, v21
	v_mul_f32_e32 v18, v18, v18
	v_mul_f32_e32 v19, v19, v19
	v_max_f32_e32 v4, 0, v4
	v_max_f32_e32 v5, 0, v5
	v_mul_f32_e32 v2, v2, v2
	v_mul_f32_e32 v3, v3, v3
	ds_write_b64 v102, v[50:51]
	v_mul_f32_e32 v50, v62, v130
	v_mul_f32_e32 v51, v63, v130
	v_mul_f32_e32 v34, v34, v130
	v_mul_f32_e32 v35, v35, v130
	v_cvt_pk_bf16_f32 v18, v18, v19
	v_mul_f32_e32 v19, v20, v20
	v_mul_f32_e32 v20, v21, v21
	v_cvt_pk_bf16_f32 v2, v2, v3
	v_mul_f32_e32 v3, v4, v4
	v_mul_f32_e32 v4, v5, v5
	v_max_f32_e32 v50, 0, v50
	v_max_f32_e32 v51, 0, v51
	v_mul_f32_e32 v52, v64, v130
	v_mul_f32_e32 v53, v65, v130
	v_max_f32_e32 v34, 0, v34
	v_max_f32_e32 v35, 0, v35
	v_mul_f32_e32 v36, v36, v130
	v_mul_f32_e32 v37, v37, v130
	v_cvt_pk_bf16_f32 v19, v19, v20
	v_cvt_pk_bf16_f32 v3, v3, v4
	v_max_f32_e32 v52, 0, v52
	v_max_f32_e32 v53, 0, v53
	v_mul_f32_e32 v50, v50, v50
	v_mul_f32_e32 v51, v51, v51
	v_max_f32_e32 v36, 0, v36
	v_max_f32_e32 v37, 0, v37
	v_mul_f32_e32 v34, v34, v34
	v_mul_f32_e32 v35, v35, v35
	ds_write_b64 v103, v[18:19] offset:4096
	ds_write_b64 v104, v[2:3] offset:4096
	v_mul_f32_e32 v2, v6, v131
	v_mul_f32_e32 v3, v7, v131
	v_cvt_pk_bf16_f32 v50, v50, v51
	v_mul_f32_e32 v51, v52, v52
	v_mul_f32_e32 v52, v53, v53
	v_cvt_pk_bf16_f32 v34, v34, v35
	v_mul_f32_e32 v35, v36, v36
	v_mul_f32_e32 v36, v37, v37
	v_max_f32_e32 v2, 0, v2
	v_max_f32_e32 v3, 0, v3
	v_mul_f32_e32 v4, v8, v131
	v_mul_f32_e32 v5, v9, v131
	v_cvt_pk_bf16_f32 v51, v51, v52
	v_cvt_pk_bf16_f32 v35, v35, v36
	v_max_f32_e32 v4, 0, v4
	v_max_f32_e32 v5, 0, v5
	v_mul_f32_e32 v2, v2, v2
	v_mul_f32_e32 v3, v3, v3
	ds_write_b64 v103, v[50:51]
	ds_write_b64 v104, v[34:35]
	v_mul_f32_e32 v34, v38, v130
	v_mul_f32_e32 v35, v39, v130
	v_cvt_pk_bf16_f32 v2, v2, v3
	v_mul_f32_e32 v3, v4, v4
	v_mul_f32_e32 v4, v5, v5
	v_max_f32_e32 v34, 0, v34
	v_max_f32_e32 v35, 0, v35
	v_mul_f32_e32 v36, v40, v130
	v_mul_f32_e32 v37, v41, v130
	v_cvt_pk_bf16_f32 v3, v3, v4
	v_max_f32_e32 v36, 0, v36
	v_max_f32_e32 v37, 0, v37
	v_mul_f32_e32 v34, v34, v34
	v_mul_f32_e32 v35, v35, v35
	ds_write_b64 v105, v[2:3] offset:4096
	v_mul_f32_e32 v2, v10, v131
	v_mul_f32_e32 v3, v11, v131
	v_cvt_pk_bf16_f32 v34, v34, v35
	v_mul_f32_e32 v35, v36, v36
	v_mul_f32_e32 v36, v37, v37
	v_max_f32_e32 v2, 0, v2
	v_max_f32_e32 v3, 0, v3
	v_mul_f32_e32 v4, v12, v131
	v_mul_f32_e32 v5, v13, v131
	v_cvt_pk_bf16_f32 v35, v35, v36
	v_max_f32_e32 v4, 0, v4
	v_max_f32_e32 v5, 0, v5
	v_mul_f32_e32 v2, v2, v2
	v_mul_f32_e32 v3, v3, v3
	ds_write_b64 v105, v[34:35]
	v_mul_f32_e32 v34, v42, v130
	v_mul_f32_e32 v35, v43, v130
	v_cvt_pk_bf16_f32 v2, v2, v3
	v_mul_f32_e32 v3, v4, v4
	v_mul_f32_e32 v4, v5, v5
	v_max_f32_e32 v34, 0, v34
	v_max_f32_e32 v35, 0, v35
	v_mul_f32_e32 v36, v44, v130
	v_mul_f32_e32 v37, v45, v130
	v_cvt_pk_bf16_f32 v3, v3, v4
	v_max_f32_e32 v36, 0, v36
	v_max_f32_e32 v37, 0, v37
	v_mul_f32_e32 v34, v34, v34
	v_mul_f32_e32 v35, v35, v35
	ds_write_b64 v106, v[2:3] offset:4096
	v_mul_f32_e32 v2, v14, v131
	v_mul_f32_e32 v3, v15, v131
	v_cvt_pk_bf16_f32 v34, v34, v35
	v_mul_f32_e32 v35, v36, v36
	v_mul_f32_e32 v36, v37, v37
	v_max_f32_e32 v2, 0, v2
	v_max_f32_e32 v3, 0, v3
	v_mul_f32_e32 v4, v16, v131
	v_mul_f32_e32 v5, v17, v131
	v_cvt_pk_bf16_f32 v35, v35, v36
	v_max_f32_e32 v4, 0, v4
	v_max_f32_e32 v5, 0, v5
	v_mul_f32_e32 v2, v2, v2
	v_mul_f32_e32 v3, v3, v3
	ds_write_b64 v106, v[34:35]
	v_mul_f32_e32 v34, v46, v130
	v_mul_f32_e32 v35, v47, v130
	v_cvt_pk_bf16_f32 v2, v2, v3
	v_mul_f32_e32 v3, v4, v4
	v_mul_f32_e32 v4, v5, v5
	v_max_f32_e32 v34, 0, v34
	v_max_f32_e32 v35, 0, v35
	v_mul_f32_e32 v36, v48, v130
	v_mul_f32_e32 v37, v49, v130
	v_cvt_pk_bf16_f32 v3, v3, v4
	v_max_f32_e32 v36, 0, v36
	v_max_f32_e32 v37, 0, v37
	v_mul_f32_e32 v34, v34, v34
	v_mul_f32_e32 v35, v35, v35
	ds_write_b64 v107, v[2:3] offset:4096
	v_or_b32_e32 v2, 64, v132
	v_cvt_pk_bf16_f32 v34, v34, v35
	v_mul_f32_e32 v35, v36, v36
	v_mul_f32_e32 v36, v37, v37
	v_ashrrev_i32_e32 v3, 31, v2
	v_cvt_pk_bf16_f32 v35, v35, v36
	v_lshlrev_b64 v[2:3], 13, v[2:3]
	ds_write_b64 v107, v[34:35]
	v_lshl_add_u64 v[2:3], s[4:5], 0, v[2:3]
	v_lshl_add_u64 v[6:7], v[2:3], 0, s[0:1]
	ds_read_b128 v[2:5], v154
	v_lshl_add_u64 v[6:7], v[6:7], 0, v[66:67]
	v_lshl_add_u64 v[14:15], v[6:7], 0, v[0:1]
	ds_read_b128 v[6:9], v155
	v_lshl_add_u64 v[10:11], v[14:15], 0, v[134:135]
	s_waitcnt lgkmcnt(1)
	global_store_dwordx4 v[10:11], v[2:5], off nt
	ds_read_b128 v[2:5], v156
	v_lshl_add_u64 v[10:11], v[14:15], 0, v[136:137]
	s_waitcnt lgkmcnt(1)
	global_store_dwordx4 v[10:11], v[6:9], off nt
	ds_read_b128 v[6:9], v157
	v_lshl_add_u64 v[10:11], v[14:15], 0, v[138:139]
	s_waitcnt lgkmcnt(1)
	global_store_dwordx4 v[10:11], v[2:5], off nt
	ds_read_b128 v[2:5], v158
	v_lshl_add_u64 v[10:11], v[14:15], 0, v[140:141]
	s_waitcnt lgkmcnt(1)
	global_store_dwordx4 v[10:11], v[6:9], off nt
	v_lshl_add_u64 v[10:11], v[14:15], 0, v[144:145]
	ds_read_b128 v[6:9], v159
	s_waitcnt lgkmcnt(1)
	global_store_dwordx4 v[10:11], v[2:5], off nt
	ds_read_b128 v[2:5], v160
	ds_read_b128 v[10:13], v161
	v_ashrrev_i32_e32 v143, 31, v142
	v_lshlrev_b64 v[142:143], 13, v[142:143]
	v_ashrrev_i32_e32 v147, 31, v146
	v_lshlrev_b64 v[146:147], 13, v[146:147]
	v_ashrrev_i32_e32 v149, 31, v148
	v_lshl_add_u64 v[82:83], v[80:81], 0, v[142:143]
	v_lshl_add_u64 v[16:17], v[14:15], 0, v[142:143]
	v_readlane_b32 s0, v250, 13
	v_lshlrev_b64 v[148:149], 13, v[148:149]
	global_store_dwordx4 v[82:83], v[72:75], off nt
	s_waitcnt lgkmcnt(2)
	global_store_dwordx4 v[16:17], v[6:9], off nt
	s_add_i32 s35, s35, s0
	v_lshl_add_u64 v[72:73], v[80:81], 0, v[146:147]
	v_lshl_add_u64 v[6:7], v[14:15], 0, v[146:147]
	global_store_dwordx4 v[72:73], v[68:71], off nt
	s_waitcnt lgkmcnt(1)
	global_store_dwordx4 v[6:7], v[2:5], off nt
	s_cmpk_gt_i32 s35, 0x3ff
	v_lshl_add_u64 v[68:69], v[80:81], 0, v[148:149]
	v_lshl_add_u64 v[2:3], v[14:15], 0, v[148:149]
	global_store_dwordx4 v[68:69], v[76:79], off nt
	s_waitcnt lgkmcnt(0)
	global_store_dwordx4 v[2:3], v[10:13], off nt
	s_barrier
	v_readlane_b32 s1, v250, 14
	s_cbranch_scc1 .LBB0_1622

.LBB0_1678:
	s_bfe_u32 s4, s30, 0x20003
	s_lshr_b32 s0, s30, 5
	s_lshl_b32 s0, s0, 3
	s_and_b32 s1, s30, 7
	s_add_i32 s0, s0, s1
	s_lshl_b32 s2, s0, 8
	s_ashr_i32 s3, s2, 31
	s_ashr_i32 s5, s4, 31
	s_lshl_b64 s[0:1], s[4:5], 21
	s_lshl_b64 s[6:7], s[2:3], 13
	v_readlane_b32 s8, v250, 48
	v_readlane_b32 s9, v250, 49
	s_add_u32 s8, s8, s6
	v_mov_b32_e32 v34, v172
	s_addc_u32 s9, s9, s7
	s_add_u32 s10, s28, s0
	v_lshlrev_b32_e32 v0, 4, v34
	v_ashrrev_i32_e32 v35, 3, v34
	v_and_b32_e32 v0, 0x70, v0
	s_addc_u32 s11, s29, s1
	v_lshl_or_b32 v0, v35, 13, v0
	v_lshl_add_u64 v[26:27], s[10:11], 0, v[0:1]
	s_mov_b32 s3, 0x80000
	v_add_co_u32_e32 v10, vcc, s3, v26
	v_lshl_add_u64 v[28:29], s[8:9], 0, v[0:1]
	s_nop 0
	v_addc_co_u32_e32 v11, vcc, 0, v27, vcc
	v_add_co_u32_e32 v14, vcc, s3, v28
	s_mov_b32 s3, 0x100000
	s_nop 0
	v_addc_co_u32_e32 v15, vcc, 0, v29, vcc
	v_add_co_u32_e32 v18, vcc, s3, v26
	global_load_dwordx4 v[2:5], v0, s[10:11]
	global_load_dwordx4 v[6:9], v0, s[8:9]
	v_addc_co_u32_e32 v19, vcc, 0, v27, vcc
	v_add_co_u32_e32 v22, vcc, s3, v28
	s_mov_b32 s3, 0x180000
	s_nop 0
	v_addc_co_u32_e32 v23, vcc, 0, v29, vcc
	v_add_co_u32_e32 v26, vcc, s3, v26
	global_load_dwordx4 v[10:13], v[10:11], off
	s_nop 0
	global_load_dwordx4 v[14:17], v[14:15], off
	v_addc_co_u32_e32 v27, vcc, 0, v27, vcc
	v_add_co_u32_e32 v30, vcc, s3, v28
	global_load_dwordx4 v[18:21], v[18:19], off
	s_nop 0
	global_load_dwordx4 v[22:25], v[22:23], off
	v_addc_co_u32_e32 v31, vcc, 0, v29, vcc
	global_load_dwordx4 v[26:29], v[26:27], off
	s_nop 0
	global_load_dwordx4 v[30:33], v[30:31], off
	v_readlane_b32 s8, v250, 9
	v_readlane_b32 s10, v250, 11
	v_readlane_b32 s11, v250, 12
	s_add_u32 s6, s10, s6
	s_addc_u32 s7, s11, s7
	v_readlane_b32 s5, v251, 9
	v_readlane_b32 s9, v250, 10
	s_add_u32 s8, s5, s0
	v_readlane_b32 s5, v251, 10
	s_addc_u32 s9, s5, s1
	v_readlane_b32 s5, v251, 11
	s_add_u32 s10, s5, s0
	v_readlane_b32 s5, v251, 12
	s_addc_u32 s11, s5, s1
	v_readlane_b32 s5, v251, 13
	s_add_u32 s12, s5, s0
	v_readlane_b32 s5, v251, 14
	s_addc_u32 s13, s5, s1
	v_readlane_b32 s5, v251, 15
	s_add_u32 s14, s5, s0
	v_readlane_b32 s5, v251, 16
	s_addc_u32 s15, s5, s1
	v_readlane_b32 s5, v251, 17
	s_add_u32 s16, s5, s0
	v_readlane_b32 s5, v251, 18
	s_addc_u32 s17, s5, s1
	v_readlane_b32 s5, v251, 19
	s_add_u32 s18, s5, s0
	v_readlane_b32 s5, v251, 20
	v_lshrrev_b32_e32 v36, 1, v35
	s_addc_u32 s19, s5, s1
	v_readlane_b32 s5, v251, 21
	v_xor_b32_e32 v34, v36, v34
	s_add_u32 s20, s5, s0
	v_readlane_b32 s5, v251, 22
	v_lshlrev_b32_e32 v35, 7, v35
	v_lshlrev_b32_e32 v34, 4, v34
	s_addc_u32 s21, s5, s1
	v_readlane_b32 s5, v251, 23
	v_mov_b32_e32 v66, 0
	v_and_or_b32 v192, v34, s55, v35
	s_add_u32 s22, s5, s0
	v_readlane_b32 s0, v251, 24
	s_mov_b32 s3, 0
	v_mov_b32_e32 v67, v66
	v_mov_b32_e32 v68, v66
	v_add_u32_e32 v193, 0x10000, v192
	s_addc_u32 s23, s0, s1
	s_waitcnt vmcnt(7)
	ds_write_b128 v192, v[2:5]
	s_waitcnt vmcnt(6)
	ds_write_b128 v193, v[6:9]
	s_waitcnt vmcnt(5)
	ds_write_b128 v192, v[10:13] offset:8192
	s_waitcnt vmcnt(4)
	ds_write_b128 v193, v[14:17] offset:8192
	s_waitcnt vmcnt(3)
	ds_write_b128 v192, v[18:21] offset:16384
	s_waitcnt vmcnt(2)
	ds_write_b128 v193, v[22:25] offset:16384
	s_waitcnt vmcnt(1)
	ds_write_b128 v192, v[26:29] offset:24576
	s_waitcnt vmcnt(0)
	ds_write_b128 v193, v[30:33] offset:24576
	v_mov_b32_e32 v69, v66
	v_mov_b32_e32 v70, v66
	v_mov_b32_e32 v71, v66
	v_mov_b32_e32 v72, v66
	v_mov_b32_e32 v73, v66
	v_mov_b32_e32 v74, v66
	v_mov_b32_e32 v75, v66
	v_mov_b32_e32 v76, v66
	v_mov_b32_e32 v77, v66
	v_mov_b32_e32 v78, v66
	v_mov_b32_e32 v79, v66
	v_mov_b32_e32 v80, v66
	v_mov_b32_e32 v81, v66
	v_mov_b32_e32 v82, v66
	v_mov_b32_e32 v83, v66
	v_mov_b32_e32 v84, v66
	v_mov_b32_e32 v85, v66
	v_mov_b32_e32 v86, v66
	v_mov_b32_e32 v87, v66
	v_mov_b32_e32 v88, v66
	v_mov_b32_e32 v89, v66
	v_mov_b32_e32 v90, v66
	v_mov_b32_e32 v91, v66
	v_mov_b32_e32 v92, v66
	v_mov_b32_e32 v93, v66
	v_mov_b32_e32 v94, v66
	v_mov_b32_e32 v95, v66
	v_mov_b32_e32 v96, v66
	v_mov_b32_e32 v97, v66
	v_mov_b32_e32 v18, v66
	v_mov_b32_e32 v19, v66
	v_mov_b32_e32 v20, v66
	v_mov_b32_e32 v21, v66
	v_mov_b32_e32 v22, v66
	v_mov_b32_e32 v23, v66
	v_mov_b32_e32 v24, v66
	v_mov_b32_e32 v25, v66
	v_mov_b32_e32 v26, v66
	v_mov_b32_e32 v27, v66
	v_mov_b32_e32 v28, v66
	v_mov_b32_e32 v29, v66
	v_mov_b32_e32 v30, v66
	v_mov_b32_e32 v31, v66
	v_mov_b32_e32 v32, v66
	v_mov_b32_e32 v33, v66
	v_mov_b32_e32 v2, v66
	v_mov_b32_e32 v3, v66
	v_mov_b32_e32 v4, v66
	v_mov_b32_e32 v5, v66
	v_mov_b32_e32 v6, v66
	v_mov_b32_e32 v7, v66
	v_mov_b32_e32 v8, v66
	v_mov_b32_e32 v9, v66
	v_mov_b32_e32 v10, v66
	v_mov_b32_e32 v11, v66
	v_mov_b32_e32 v12, v66
	v_mov_b32_e32 v13, v66
	v_mov_b32_e32 v14, v66
	v_mov_b32_e32 v15, v66
	v_mov_b32_e32 v16, v66
	v_mov_b32_e32 v17, v66
	v_mov_b32_e32 v114, v66
	v_mov_b32_e32 v115, v66
	v_mov_b32_e32 v116, v66
	v_mov_b32_e32 v117, v66
	v_mov_b32_e32 v118, v66
	v_mov_b32_e32 v119, v66
	v_mov_b32_e32 v120, v66
	v_mov_b32_e32 v121, v66
	v_mov_b32_e32 v122, v66
	v_mov_b32_e32 v123, v66
	v_mov_b32_e32 v124, v66
	v_mov_b32_e32 v125, v66
	v_mov_b32_e32 v126, v66
	v_mov_b32_e32 v127, v66
	v_mov_b32_e32 v128, v66
	v_mov_b32_e32 v129, v66
	v_mov_b32_e32 v98, v66
	v_mov_b32_e32 v99, v66
	v_mov_b32_e32 v100, v66
	v_mov_b32_e32 v101, v66
	v_mov_b32_e32 v102, v66
	v_mov_b32_e32 v103, v66
	v_mov_b32_e32 v104, v66
	v_mov_b32_e32 v105, v66
	v_mov_b32_e32 v106, v66
	v_mov_b32_e32 v107, v66
	v_mov_b32_e32 v108, v66
	v_mov_b32_e32 v109, v66
	v_mov_b32_e32 v110, v66
	v_mov_b32_e32 v111, v66
	v_mov_b32_e32 v112, v66
	v_mov_b32_e32 v113, v66
	v_mov_b32_e32 v50, v66
	v_mov_b32_e32 v51, v66
	v_mov_b32_e32 v52, v66
	v_mov_b32_e32 v53, v66
	v_mov_b32_e32 v54, v66
	v_mov_b32_e32 v55, v66
	v_mov_b32_e32 v56, v66
	v_mov_b32_e32 v57, v66
	v_mov_b32_e32 v58, v66
	v_mov_b32_e32 v59, v66
	v_mov_b32_e32 v60, v66
	v_mov_b32_e32 v61, v66
	v_mov_b32_e32 v62, v66
	v_mov_b32_e32 v63, v66
	v_mov_b32_e32 v64, v66
	v_mov_b32_e32 v65, v66
	v_mov_b32_e32 v34, v66
	v_mov_b32_e32 v35, v66
	v_mov_b32_e32 v36, v66
	v_mov_b32_e32 v37, v66
	v_mov_b32_e32 v38, v66
	v_mov_b32_e32 v39, v66
	v_mov_b32_e32 v40, v66
	v_mov_b32_e32 v41, v66
	v_mov_b32_e32 v42, v66
	v_mov_b32_e32 v43, v66
	v_mov_b32_e32 v44, v66
	v_mov_b32_e32 v45, v66
	v_mov_b32_e32 v46, v66
	v_mov_b32_e32 v47, v66
	v_mov_b32_e32 v48, v66
	v_mov_b32_e32 v49, v66
	s_waitcnt lgkmcnt(0)
	s_barrier
	s_add_u32 s10, s8, 0x80000
	s_addc_u32 s11, s9, 0
	s_add_u32 s12, s8, 0x100000
	s_addc_u32 s13, s9, 0
	s_add_u32 s14, s8, 0x180000
	s_addc_u32 s15, s9, 0
	s_add_u32 s16, s6, 0x7800080
	s_addc_u32 s17, s7, 0
	s_add_u32 s18, s16, 0x80000
	s_addc_u32 s19, s17, 0
	s_add_u32 s20, s16, 0x100000
	s_addc_u32 s21, s17, 0
	s_add_u32 s22, s16, 0x180000
	s_addc_u32 s23, s17, 0
	v_lshrrev_b32_e32 v170, 3, v204
	v_lshrrev_b32_e32 v171, 4, v204
	v_xor_b32_e32 v171, v171, v204
	v_and_b32_e32 v171, 7, v171
	v_lshlrev_b32_e32 v171, 4, v171
	v_lshl_or_b32 v170, v170, 13, v171
	v_readfirstlane_b32 s24, v204
	s_and_b32 s24, s24, 0x3c0
	s_lshl_b32 s24, s24, 4
	s_mov_b32 s3, 0
	ds_read_b128 v[130:133], v184
	ds_read_b128 v[138:141], v180
	ds_read_b128 v[134:137], v184 offset:4096
	ds_read_b128 v[142:145], v180 offset:4096
	ds_read_b128 v[146:149], v180 offset:8192
	ds_read_b128 v[150:153], v180 offset:12288
	s_add_u32 m0, s24, 0x8000
	s_nop 0
	global_load_lds_dwordx4 v170, s[8:9]
	s_add_u32 m0, s24, 0x18000
	s_nop 0
	global_load_lds_dwordx4 v170, s[16:17] nt
	s_add_u32 m0, s24, 0xa000
	s_nop 0
	global_load_lds_dwordx4 v170, s[10:11]
	s_add_u32 m0, s24, 0x1a000
	s_nop 0
	global_load_lds_dwordx4 v170, s[18:19] nt
	s_add_u32 m0, s24, 0xc000
	s_nop 0
	global_load_lds_dwordx4 v170, s[12:13]
	s_add_u32 m0, s24, 0x1c000
	s_nop 0
	global_load_lds_dwordx4 v170, s[20:21] nt
	s_add_u32 m0, s24, 0xe000
	s_nop 0
	global_load_lds_dwordx4 v170, s[14:15]
	s_add_u32 m0, s24, 0x1e000
	s_nop 0
	global_load_lds_dwordx4 v170, s[22:23] nt
	s_branch .Lg_mlp2_mid
.Lg_mlp2_top:
	ds_read_b128 v[130:133], v184
	ds_read_b128 v[138:141], v180
	ds_read_b128 v[134:137], v184 offset:4096
	ds_read_b128 v[142:145], v180 offset:4096
	ds_read_b128 v[146:149], v180 offset:8192
	ds_read_b128 v[150:153], v180 offset:12288
	s_add_u32 m0, s24, 0x8000
	v_mfma_f32_32x32x16_bf16 v[66:81], v[154:157], v[162:165], v[66:81]
	global_load_lds_dwordx4 v170, s[8:9]
	s_add_u32 m0, s24, 0x18000
	v_mfma_f32_32x32x16_bf16 v[114:129], v[158:161], v[162:165], v[114:129]
	global_load_lds_dwordx4 v170, s[16:17] nt
	s_add_u32 m0, s24, 0xa000
	v_mfma_f32_32x32x16_bf16 v[82:97], v[154:157], v[166:169], v[82:97]
	global_load_lds_dwordx4 v170, s[10:11]
	s_add_u32 m0, s24, 0x1a000
	v_mfma_f32_32x32x16_bf16 v[98:113], v[158:161], v[166:169], v[98:113]
	global_load_lds_dwordx4 v170, s[18:19] nt
	s_add_u32 m0, s24, 0xc000
	v_mfma_f32_32x32x16_bf16 v[18:33], v[154:157], v[194:197], v[18:33]
	global_load_lds_dwordx4 v170, s[12:13]
	s_add_u32 m0, s24, 0x1c000
	v_mfma_f32_32x32x16_bf16 v[50:65], v[158:161], v[194:197], v[50:65]
	global_load_lds_dwordx4 v170, s[20:21] nt
	s_add_u32 m0, s24, 0xe000
	v_mfma_f32_32x32x16_bf16 v[2:17], v[154:157], v[198:201], v[2:17]
	global_load_lds_dwordx4 v170, s[14:15]
	s_add_u32 m0, s24, 0x1e000
	v_mfma_f32_32x32x16_bf16 v[34:49], v[158:161], v[198:201], v[34:49]
	global_load_lds_dwordx4 v170, s[22:23] nt

.Lg_mlp2_mid2:
	ds_read_b128 v[130:133], v186
	ds_read_b128 v[138:141], v182
	ds_read_b128 v[134:137], v186 offset:4096
	ds_read_b128 v[142:145], v182 offset:4096
	ds_read_b128 v[146:149], v182 offset:8192
	ds_read_b128 v[150:153], v182 offset:12288
	s_waitcnt lgkmcnt(6)
	v_mfma_f32_32x32x16_bf16 v[66:81], v[154:157], v[162:165], v[66:81]
	v_mfma_f32_32x32x16_bf16 v[114:129], v[158:161], v[162:165], v[114:129]
	v_mfma_f32_32x32x16_bf16 v[82:97], v[154:157], v[166:169], v[82:97]
	v_mfma_f32_32x32x16_bf16 v[98:113], v[158:161], v[166:169], v[98:113]
	v_mfma_f32_32x32x16_bf16 v[18:33], v[154:157], v[194:197], v[18:33]
	v_mfma_f32_32x32x16_bf16 v[50:65], v[158:161], v[194:197], v[50:65]
	v_mfma_f32_32x32x16_bf16 v[2:17], v[154:157], v[198:201], v[2:17]
	v_mfma_f32_32x32x16_bf16 v[34:49], v[158:161], v[198:201], v[34:49]
	ds_read_b128 v[154:157], v187
	ds_read_b128 v[162:165], v183
	ds_read_b128 v[158:161], v187 offset:4096
	ds_read_b128 v[166:169], v183 offset:4096
	ds_read_b128 v[194:197], v183 offset:8192
	ds_read_b128 v[198:201], v183 offset:12288
	s_waitcnt lgkmcnt(6)
	v_mfma_f32_32x32x16_bf16 v[66:81], v[130:133], v[138:141], v[66:81]
	v_mfma_f32_32x32x16_bf16 v[114:129], v[134:137], v[138:141], v[114:129]
	v_mfma_f32_32x32x16_bf16 v[82:97], v[130:133], v[142:145], v[82:97]
	v_mfma_f32_32x32x16_bf16 v[98:113], v[134:137], v[142:145], v[98:113]
	v_mfma_f32_32x32x16_bf16 v[18:33], v[130:133], v[146:149], v[18:33]
	v_mfma_f32_32x32x16_bf16 v[50:65], v[134:137], v[146:149], v[50:65]
	v_mfma_f32_32x32x16_bf16 v[2:17], v[130:133], v[150:153], v[2:17]
	v_mfma_f32_32x32x16_bf16 v[34:49], v[134:137], v[150:153], v[34:49]
	s_waitcnt vmcnt(0) lgkmcnt(0)
	s_barrier
	ds_read_b128 v[130:133], v184 offset:32768
	ds_read_b128 v[138:141], v188
	ds_read_b128 v[134:137], v184 offset:36864
	ds_read_b128 v[142:145], v188 offset:4096
	ds_read_b128 v[146:149], v188 offset:8192
	ds_read_b128 v[150:153], v188 offset:12288
	s_cmp_ge_u32 s3, 62
	s_cbranch_scc1 .Lg_mlp2_nodma
	s_add_u32 m0, s24, 0x0
	v_mfma_f32_32x32x16_bf16 v[66:81], v[154:157], v[162:165], v[66:81]
	global_load_lds_dwordx4 v170, s[8:9]
	s_add_u32 m0, s24, 0x10000
	v_mfma_f32_32x32x16_bf16 v[114:129], v[158:161], v[162:165], v[114:129]
	global_load_lds_dwordx4 v170, s[16:17] nt
	s_add_u32 m0, s24, 0x2000
	v_mfma_f32_32x32x16_bf16 v[82:97], v[154:157], v[166:169], v[82:97]
	global_load_lds_dwordx4 v170, s[10:11]
	s_add_u32 m0, s24, 0x12000
	v_mfma_f32_32x32x16_bf16 v[98:113], v[158:161], v[166:169], v[98:113]
	global_load_lds_dwordx4 v170, s[18:19] nt
	s_add_u32 m0, s24, 0x4000
	v_mfma_f32_32x32x16_bf16 v[18:33], v[154:157], v[194:197], v[18:33]
	global_load_lds_dwordx4 v170, s[12:13]
	s_add_u32 m0, s24, 0x14000
	v_mfma_f32_32x32x16_bf16 v[50:65], v[158:161], v[194:197], v[50:65]
	global_load_lds_dwordx4 v170, s[20:21] nt
	s_add_u32 m0, s24, 0x6000
	v_mfma_f32_32x32x16_bf16 v[2:17], v[154:157], v[198:201], v[2:17]
	global_load_lds_dwordx4 v170, s[14:15]
	s_add_u32 m0, s24, 0x16000
	v_mfma_f32_32x32x16_bf16 v[34:49], v[158:161], v[198:201], v[34:49]
	global_load_lds_dwordx4 v170, s[22:23] nt
	s_branch .Lg_mlp2_join
